# phase 13 conv+transpose rewritten by hand: tile rows and conv weights requested two tiles ahead (two register sets), peeled first/last pair + 10-iteration pair loop, exact counted waits; same LDS imag
# baseline (speedup 1.0000x reference)
.LBB0_256:
	v_readlane_b32 s2, v249, 14
	v_readlane_b32 s3, v249, 15
	v_readlane_b32 s4, v251, 10
	v_readlane_b32 s5, v251, 11
	v_readlane_b32 s6, v251, 12
	v_readlane_b32 s7, v251, 13
	v_readlane_b32 s8, v255, 6
	v_readlane_b32 s9, v249, 18
	v_lshrrev_b32_e32 v114, 4, v163
	v_and_b32_e32 v115, 15, v163
	v_mul_u32_u24_e32 v104, 0x1800, v114
	v_lshl_add_u32 v104, v115, 4, v104
	v_add_u32_e32 v116, 0, v114
	v_lshrrev_b32_e32 v117, 3, v116
	v_add_lshl_u32 v117, v117, v115, 2
	v_and_b32_e32 v117, 63, v117
	v_lshl_add_u32 v117, v116, 6, v117
	v_lshlrev_b32_e32 v48, 2, v117
	v_add_u32_e32 v116, 32, v114
	v_lshrrev_b32_e32 v117, 3, v116
	v_add_lshl_u32 v117, v117, v115, 2
	v_and_b32_e32 v117, 63, v117
	v_lshl_add_u32 v117, v116, 6, v117
	v_lshlrev_b32_e32 v49, 2, v117
	v_add_u32_e32 v116, 64, v114
	v_lshrrev_b32_e32 v117, 3, v116
	v_add_lshl_u32 v117, v117, v115, 2
	v_and_b32_e32 v117, 63, v117
	v_lshl_add_u32 v117, v116, 6, v117
	v_lshlrev_b32_e32 v50, 2, v117
	v_add_u32_e32 v116, 96, v114
	v_lshrrev_b32_e32 v117, 3, v116
	v_add_lshl_u32 v117, v117, v115, 2
	v_and_b32_e32 v117, 63, v117
	v_lshl_add_u32 v117, v116, 6, v117
	v_lshlrev_b32_e32 v51, 2, v117
	v_add_u32_e32 v118, 0, v114
	v_lshl_add_u32 v119, v115, 2, v118
	v_and_b32_e32 v119, 63, v119
	v_lshl_add_u32 v119, v115, 9, v119
	v_lshlrev_b32_e32 v53, 2, v119
	v_lshl_add_u32 v119, v115, 2, v118
	v_add_u32_e32 v119, -4, v119
	v_and_b32_e32 v119, 63, v119
	v_lshlrev_b32_e32 v120, 9, v115
	v_add_u32_e32 v120, -64, v120
	v_add_lshl_u32 v52, v120, v119, 2
	v_lshl_add_u32 v119, v115, 2, v118
	v_add_u32_e32 v119, 4, v119
	v_and_b32_e32 v119, 63, v119
	v_lshlrev_b32_e32 v120, 9, v115
	v_add_u32_e32 v120, 0x200, v120
	v_add_lshl_u32 v54, v120, v119, 2
	v_lshlrev_b32_e32 v106, 15, v118
	v_lshl_add_u32 v106, v115, 4, v106
	v_add_u32_e32 v107, 0x4000, v106
	v_lshlrev_b32_e32 v110, 3, v118
	v_add_u32_e32 v118, 32, v114
	v_lshl_add_u32 v119, v115, 2, v118
	v_and_b32_e32 v119, 63, v119
	v_lshl_add_u32 v119, v115, 9, v119
	v_lshlrev_b32_e32 v56, 2, v119
	v_lshl_add_u32 v119, v115, 2, v118
	v_add_u32_e32 v119, -4, v119
	v_and_b32_e32 v119, 63, v119
	v_lshlrev_b32_e32 v120, 9, v115
	v_add_u32_e32 v120, -64, v120
	v_add_lshl_u32 v55, v120, v119, 2
	v_lshl_add_u32 v119, v115, 2, v118
	v_add_u32_e32 v119, 4, v119
	v_and_b32_e32 v119, 63, v119
	v_lshlrev_b32_e32 v120, 9, v115
	v_add_u32_e32 v120, 0x200, v120
	v_add_lshl_u32 v57, v120, v119, 2
	v_lshlrev_b32_e32 v108, 15, v118
	v_lshl_add_u32 v108, v115, 4, v108
	v_add_u32_e32 v109, 0x4000, v108
	v_lshlrev_b32_e32 v111, 3, v118
	v_and_b32_e32 v119, 7, v115
	v_cmp_ne_u32_e64 s[20:21], 0, v119
	v_cmp_ne_u32_e64 s[22:23], 7, v119
	s_nop 1
	v_cndmask_b32_e64 v52, v53, v52, s[20:21]
	v_cndmask_b32_e64 v54, v53, v54, s[22:23]
	s_nop 1
	v_cndmask_b32_e64 v55, v56, v55, s[20:21]
	v_cndmask_b32_e64 v57, v56, v57, s[22:23]
	s_mul_hi_u32 s12, s8, 0xAAAAAAAB
	s_lshr_b32 s12, s12, 4
	s_mul_i32 s24, s12, 24
	s_sub_u32 s10, s8, s24
	s_mul_hi_u32 s14, s9, 0xAAAAAAAB
	s_lshr_b32 s14, s14, 4
	s_mul_i32 s24, s14, 24
	s_sub_u32 s13, s9, s24
	s_mov_b32 s15, 0
	s_waitcnt vmcnt(0) lgkmcnt(0)
	s_mov_b32 s26, s10
	s_mov_b32 s27, s12
	s_mul_i32 s24, s12, 0xC0000
	s_lshl_b32 s25, s10, 8
	s_add_u32 s24, s24, s25
	s_add_u32 s24, s24, 0x8000000
	s_add_u32 s16, s2, s24
	s_addc_u32 s17, s3, 0
	s_lshl_b32 s25, s10, 9
	v_add_u32_e32 v112, s25, v110
	v_add_u32_e32 v113, s25, v111
	global_load_dwordx2 v[22:23], v112, s[6:7]
	global_load_dwordx2 v[16:17], v112, s[4:5]
	v_add_u32_e32 v112, 0x3000, v112
	global_load_dwordx2 v[18:19], v112, s[4:5]
	v_add_u32_e32 v112, 0x3000, v112
	global_load_dwordx2 v[20:21], v112, s[4:5]
	global_load_dwordx2 v[30:31], v113, s[6:7]
	global_load_dwordx2 v[24:25], v113, s[4:5]
	v_add_u32_e32 v113, 0x3000, v113
	global_load_dwordx2 v[26:27], v113, s[4:5]
	v_add_u32_e32 v113, 0x3000, v113
	global_load_dwordx2 v[28:29], v113, s[4:5]
	v_mov_b32_e32 v105, v104
	global_load_dwordx4 v[0:3], v105, s[16:17] nt
	v_add_u32_e32 v105, 0x30000, v105
	global_load_dwordx4 v[4:7], v105, s[16:17] nt
	v_add_u32_e32 v105, 0x30000, v105
	global_load_dwordx4 v[8:11], v105, s[16:17] nt
	v_add_u32_e32 v105, 0x30000, v105
	global_load_dwordx4 v[12:15], v105, s[16:17] nt
	s_add_u32 s10, s10, s13
	s_add_u32 s12, s12, s14
	s_cmp_ge_u32 s10, 24
	s_cbranch_scc0 .LcT2_nw1
	s_sub_u32 s10, s10, 24
	s_add_u32 s12, s12, 1
.LcT2_nw1:
	s_mul_i32 s24, s12, 0xC0000
	s_lshl_b32 s25, s10, 8
	s_add_u32 s24, s24, s25
	s_add_u32 s24, s24, 0x8000000
	s_add_u32 s16, s2, s24
	s_addc_u32 s17, s3, 0
	s_lshl_b32 s25, s10, 9
	v_add_u32_e32 v112, s25, v110
	v_add_u32_e32 v113, s25, v111
	global_load_dwordx2 v[174:175], v112, s[6:7]
	global_load_dwordx2 v[168:169], v112, s[4:5]
	v_add_u32_e32 v112, 0x3000, v112
	global_load_dwordx2 v[170:171], v112, s[4:5]
	v_add_u32_e32 v112, 0x3000, v112
	global_load_dwordx2 v[172:173], v112, s[4:5]
	global_load_dwordx2 v[182:183], v113, s[6:7]
	global_load_dwordx2 v[176:177], v113, s[4:5]
	v_add_u32_e32 v113, 0x3000, v113
	global_load_dwordx2 v[178:179], v113, s[4:5]
	v_add_u32_e32 v113, 0x3000, v113
	global_load_dwordx2 v[180:181], v113, s[4:5]
	v_mov_b32_e32 v105, v104
	global_load_dwordx4 v[136:139], v105, s[16:17] nt
	v_add_u32_e32 v105, 0x30000, v105
	global_load_dwordx4 v[140:143], v105, s[16:17] nt
	v_add_u32_e32 v105, 0x30000, v105
	global_load_dwordx4 v[144:147], v105, s[16:17] nt
	v_add_u32_e32 v105, 0x30000, v105
	global_load_dwordx4 v[148:151], v105, s[16:17] nt
	s_add_u32 s10, s10, s13
	s_add_u32 s12, s12, s14
	s_cmp_ge_u32 s10, 24
	s_cbranch_scc0 .LcT2_nw2
	s_sub_u32 s10, s10, 24
	s_add_u32 s12, s12, 1
.LcT2_nw2:
	s_barrier
	s_lshr_b32 s24, s26, 3
	s_lshl_b32 s24, s24, 2
	s_lshr_b32 s25, s27, 6
	s_add_u32 s24, s24, s25
	s_lshl_b32 s24, s24, 24
	s_and_b32 s25, s26, 7
	s_lshl_b32 s25, s25, 21
	s_add_u32 s24, s24, s25
	s_and_b32 s25, s27, 63
	s_lshl_b32 s25, s25, 8
	s_add_u32 s24, s24, s25
	s_add_u32 s24, s24, 0x14000000
	s_add_u32 s18, s2, s24
	s_addc_u32 s19, s3, 0
	s_add_u32 s26, s26, s13
	s_add_u32 s27, s27, s14
	s_cmp_ge_u32 s26, 24
	s_cbranch_scc0 .LcT2_nw3
	s_sub_u32 s26, s26, 24
	s_add_u32 s27, s27, 1
.LcT2_nw3:
	s_waitcnt vmcnt(12)
	v_mov_b32_e32 v32, v16
	v_mov_b32_e32 v33, v17
	v_mov_b32_e32 v34, v18
	v_mov_b32_e32 v35, v19
	v_mov_b32_e32 v36, v20
	v_mov_b32_e32 v37, v21
	v_mov_b32_e32 v38, v22
	v_mov_b32_e32 v39, v23
	v_mov_b32_e32 v40, v24
	v_mov_b32_e32 v41, v25
	v_mov_b32_e32 v42, v26
	v_mov_b32_e32 v43, v27
	v_mov_b32_e32 v44, v28
	v_mov_b32_e32 v45, v29
	v_mov_b32_e32 v46, v30
	v_mov_b32_e32 v47, v31
	ds_write_b128 v48, v[0:3]
	ds_write_b128 v49, v[4:7]
	ds_write_b128 v50, v[8:11]
	ds_write_b128 v51, v[12:15]
	s_mul_i32 s24, s12, 0xC0000
	s_lshl_b32 s25, s10, 8
	s_add_u32 s24, s24, s25
	s_add_u32 s24, s24, 0x8000000
	s_add_u32 s16, s2, s24
	s_addc_u32 s17, s3, 0
	s_lshl_b32 s25, s10, 9
	v_add_u32_e32 v112, s25, v110
	v_add_u32_e32 v113, s25, v111
	global_load_dwordx2 v[22:23], v112, s[6:7]
	global_load_dwordx2 v[16:17], v112, s[4:5]
	v_add_u32_e32 v112, 0x3000, v112
	global_load_dwordx2 v[18:19], v112, s[4:5]
	v_add_u32_e32 v112, 0x3000, v112
	global_load_dwordx2 v[20:21], v112, s[4:5]
	global_load_dwordx2 v[30:31], v113, s[6:7]
	global_load_dwordx2 v[24:25], v113, s[4:5]
	v_add_u32_e32 v113, 0x3000, v113
	global_load_dwordx2 v[26:27], v113, s[4:5]
	v_add_u32_e32 v113, 0x3000, v113
	global_load_dwordx2 v[28:29], v113, s[4:5]
	v_mov_b32_e32 v105, v104
	global_load_dwordx4 v[0:3], v105, s[16:17] nt
	v_add_u32_e32 v105, 0x30000, v105
	global_load_dwordx4 v[4:7], v105, s[16:17] nt
	v_add_u32_e32 v105, 0x30000, v105
	global_load_dwordx4 v[8:11], v105, s[16:17] nt
	v_add_u32_e32 v105, 0x30000, v105
	global_load_dwordx4 v[12:15], v105, s[16:17] nt
	s_add_u32 s10, s10, s13
	s_add_u32 s12, s12, s14
	s_cmp_ge_u32 s10, 24
	s_cbranch_scc0 .LcT2_nw4
	s_sub_u32 s10, s10, 24
	s_add_u32 s12, s12, 1
.LcT2_nw4:
	s_waitcnt lgkmcnt(0)
	s_barrier
	ds_read_b32 v123, v52
	ds_read2st64_b32 v[124:125], v53 offset0:0 offset1:1
	ds_read2st64_b32 v[126:127], v53 offset0:2 offset1:3
	ds_read2st64_b32 v[128:129], v53 offset0:4 offset1:5
	ds_read2st64_b32 v[130:131], v53 offset0:6 offset1:7
	ds_read_b32 v132, v54
	s_waitcnt lgkmcnt(0)
	v_cndmask_b32_e64 v123, 0, v123, s[20:21]
	v_cndmask_b32_e64 v132, 0, v132, s[22:23]
	v_lshlrev_b32_e32 v60, 16, v123
	v_and_b32_e32 v61, 0xffff0000, v123
	v_lshlrev_b32_e32 v62, 16, v124
	v_and_b32_e32 v63, 0xffff0000, v124
	v_lshlrev_b32_e32 v64, 16, v125
	v_and_b32_e32 v65, 0xffff0000, v125
	v_lshlrev_b32_e32 v66, 16, v126
	v_and_b32_e32 v67, 0xffff0000, v126
	v_lshlrev_b32_e32 v68, 16, v127
	v_and_b32_e32 v69, 0xffff0000, v127
	v_lshlrev_b32_e32 v70, 16, v128
	v_and_b32_e32 v71, 0xffff0000, v128
	v_lshlrev_b32_e32 v72, 16, v129
	v_and_b32_e32 v73, 0xffff0000, v129
	v_lshlrev_b32_e32 v74, 16, v130
	v_and_b32_e32 v75, 0xffff0000, v130
	v_lshlrev_b32_e32 v76, 16, v131
	v_and_b32_e32 v77, 0xffff0000, v131
	v_lshlrev_b32_e32 v78, 16, v132
	v_and_b32_e32 v79, 0xffff0000, v132
	v_pk_fma_f32 v[80:81], v[32:33], v[60:61], v[38:39]
	v_pk_fma_f32 v[82:83], v[32:33], v[62:63], v[38:39]
	v_pk_fma_f32 v[84:85], v[32:33], v[64:65], v[38:39]
	v_pk_fma_f32 v[86:87], v[32:33], v[66:67], v[38:39]
	v_pk_fma_f32 v[88:89], v[32:33], v[68:69], v[38:39]
	v_pk_fma_f32 v[90:91], v[32:33], v[70:71], v[38:39]
	v_pk_fma_f32 v[92:93], v[32:33], v[72:73], v[38:39]
	v_pk_fma_f32 v[94:95], v[32:33], v[74:75], v[38:39]
	v_pk_fma_f32 v[80:81], v[34:35], v[62:63], v[80:81]
	v_pk_fma_f32 v[82:83], v[34:35], v[64:65], v[82:83]
	v_pk_fma_f32 v[84:85], v[34:35], v[66:67], v[84:85]
	v_pk_fma_f32 v[86:87], v[34:35], v[68:69], v[86:87]
	v_pk_fma_f32 v[88:89], v[34:35], v[70:71], v[88:89]
	v_pk_fma_f32 v[90:91], v[34:35], v[72:73], v[90:91]
	v_pk_fma_f32 v[92:93], v[34:35], v[74:75], v[92:93]
	v_pk_fma_f32 v[94:95], v[34:35], v[76:77], v[94:95]
	v_pk_fma_f32 v[80:81], v[36:37], v[64:65], v[80:81]
	v_pk_fma_f32 v[82:83], v[36:37], v[66:67], v[82:83]
	v_pk_fma_f32 v[84:85], v[36:37], v[68:69], v[84:85]
	v_pk_fma_f32 v[86:87], v[36:37], v[70:71], v[86:87]
	v_pk_fma_f32 v[88:89], v[36:37], v[72:73], v[88:89]
	v_pk_fma_f32 v[90:91], v[36:37], v[74:75], v[90:91]
	v_pk_fma_f32 v[92:93], v[36:37], v[76:77], v[92:93]
	v_pk_fma_f32 v[94:95], v[36:37], v[78:79], v[94:95]
	v_cvt_pk_bf16_f32 v96, v80, v82
	v_cvt_pk_bf16_f32 v97, v84, v86
	v_cvt_pk_bf16_f32 v98, v88, v90
	v_cvt_pk_bf16_f32 v99, v92, v94
	v_cvt_pk_bf16_f32 v100, v81, v83
	v_cvt_pk_bf16_f32 v101, v85, v87
	v_cvt_pk_bf16_f32 v102, v89, v91
	v_cvt_pk_bf16_f32 v103, v93, v95
	global_store_dwordx4 v106, v[96:99], s[18:19]
	global_store_dwordx4 v107, v[100:103], s[18:19]
	ds_read_b32 v123, v55
	ds_read2st64_b32 v[124:125], v56 offset0:0 offset1:1
	ds_read2st64_b32 v[126:127], v56 offset0:2 offset1:3
	ds_read2st64_b32 v[128:129], v56 offset0:4 offset1:5
	ds_read2st64_b32 v[130:131], v56 offset0:6 offset1:7
	ds_read_b32 v132, v57
	s_waitcnt lgkmcnt(0)
	v_cndmask_b32_e64 v123, 0, v123, s[20:21]
	v_cndmask_b32_e64 v132, 0, v132, s[22:23]
	v_lshlrev_b32_e32 v60, 16, v123
	v_and_b32_e32 v61, 0xffff0000, v123
	v_lshlrev_b32_e32 v62, 16, v124
	v_and_b32_e32 v63, 0xffff0000, v124
	v_lshlrev_b32_e32 v64, 16, v125
	v_and_b32_e32 v65, 0xffff0000, v125
	v_lshlrev_b32_e32 v66, 16, v126
	v_and_b32_e32 v67, 0xffff0000, v126
	v_lshlrev_b32_e32 v68, 16, v127
	v_and_b32_e32 v69, 0xffff0000, v127
	v_lshlrev_b32_e32 v70, 16, v128
	v_and_b32_e32 v71, 0xffff0000, v128
	v_lshlrev_b32_e32 v72, 16, v129
	v_and_b32_e32 v73, 0xffff0000, v129
	v_lshlrev_b32_e32 v74, 16, v130
	v_and_b32_e32 v75, 0xffff0000, v130
	v_lshlrev_b32_e32 v76, 16, v131
	v_and_b32_e32 v77, 0xffff0000, v131
	v_lshlrev_b32_e32 v78, 16, v132
	v_and_b32_e32 v79, 0xffff0000, v132
	v_pk_fma_f32 v[80:81], v[40:41], v[60:61], v[46:47]
	v_pk_fma_f32 v[82:83], v[40:41], v[62:63], v[46:47]
	v_pk_fma_f32 v[84:85], v[40:41], v[64:65], v[46:47]
	v_pk_fma_f32 v[86:87], v[40:41], v[66:67], v[46:47]
	v_pk_fma_f32 v[88:89], v[40:41], v[68:69], v[46:47]
	v_pk_fma_f32 v[90:91], v[40:41], v[70:71], v[46:47]
	v_pk_fma_f32 v[92:93], v[40:41], v[72:73], v[46:47]
	v_pk_fma_f32 v[94:95], v[40:41], v[74:75], v[46:47]
	v_pk_fma_f32 v[80:81], v[42:43], v[62:63], v[80:81]
	v_pk_fma_f32 v[82:83], v[42:43], v[64:65], v[82:83]
	v_pk_fma_f32 v[84:85], v[42:43], v[66:67], v[84:85]
	v_pk_fma_f32 v[86:87], v[42:43], v[68:69], v[86:87]
	v_pk_fma_f32 v[88:89], v[42:43], v[70:71], v[88:89]
	v_pk_fma_f32 v[90:91], v[42:43], v[72:73], v[90:91]
	v_pk_fma_f32 v[92:93], v[42:43], v[74:75], v[92:93]
	v_pk_fma_f32 v[94:95], v[42:43], v[76:77], v[94:95]
	v_pk_fma_f32 v[80:81], v[44:45], v[64:65], v[80:81]
	v_pk_fma_f32 v[82:83], v[44:45], v[66:67], v[82:83]
	v_pk_fma_f32 v[84:85], v[44:45], v[68:69], v[84:85]
	v_pk_fma_f32 v[86:87], v[44:45], v[70:71], v[86:87]
	v_pk_fma_f32 v[88:89], v[44:45], v[72:73], v[88:89]
	v_pk_fma_f32 v[90:91], v[44:45], v[74:75], v[90:91]
	v_pk_fma_f32 v[92:93], v[44:45], v[76:77], v[92:93]
	v_pk_fma_f32 v[94:95], v[44:45], v[78:79], v[94:95]
	v_cvt_pk_bf16_f32 v96, v80, v82
	v_cvt_pk_bf16_f32 v97, v84, v86
	v_cvt_pk_bf16_f32 v98, v88, v90
	v_cvt_pk_bf16_f32 v99, v92, v94
	v_cvt_pk_bf16_f32 v100, v81, v83
	v_cvt_pk_bf16_f32 v101, v85, v87
	v_cvt_pk_bf16_f32 v102, v89, v91
	v_cvt_pk_bf16_f32 v103, v93, v95
	global_store_dwordx4 v108, v[96:99], s[18:19]
	global_store_dwordx4 v109, v[100:103], s[18:19]
	s_lshr_b32 s24, s26, 3
	s_lshl_b32 s24, s24, 2
	s_lshr_b32 s25, s27, 6
	s_add_u32 s24, s24, s25
	s_lshl_b32 s24, s24, 24
	s_and_b32 s25, s26, 7
	s_lshl_b32 s25, s25, 21
	s_add_u32 s24, s24, s25
	s_and_b32 s25, s27, 63
	s_lshl_b32 s25, s25, 8
	s_add_u32 s24, s24, s25
	s_add_u32 s24, s24, 0x14000000
	s_add_u32 s18, s2, s24
	s_addc_u32 s19, s3, 0
	s_add_u32 s26, s26, s13
	s_add_u32 s27, s27, s14
	s_cmp_ge_u32 s26, 24
	s_cbranch_scc0 .LcT2_nw5
	s_sub_u32 s26, s26, 24
	s_add_u32 s27, s27, 1
.LcT2_nw5:
	s_waitcnt vmcnt(16)
	v_mov_b32_e32 v32, v168
	v_mov_b32_e32 v33, v169
	v_mov_b32_e32 v34, v170
	v_mov_b32_e32 v35, v171
	v_mov_b32_e32 v36, v172
	v_mov_b32_e32 v37, v173
	v_mov_b32_e32 v38, v174
	v_mov_b32_e32 v39, v175
	v_mov_b32_e32 v40, v176
	v_mov_b32_e32 v41, v177
	v_mov_b32_e32 v42, v178
	v_mov_b32_e32 v43, v179
	v_mov_b32_e32 v44, v180
	v_mov_b32_e32 v45, v181
	v_mov_b32_e32 v46, v182
	v_mov_b32_e32 v47, v183
	ds_write_b128 v48, v[136:139] offset:32768
	ds_write_b128 v49, v[140:143] offset:32768
	ds_write_b128 v50, v[144:147] offset:32768
	ds_write_b128 v51, v[148:151] offset:32768
	s_mul_i32 s24, s12, 0xC0000
	s_lshl_b32 s25, s10, 8
	s_add_u32 s24, s24, s25
	s_add_u32 s24, s24, 0x8000000
	s_add_u32 s16, s2, s24
	s_addc_u32 s17, s3, 0
	s_lshl_b32 s25, s10, 9
	v_add_u32_e32 v112, s25, v110
	v_add_u32_e32 v113, s25, v111
	global_load_dwordx2 v[174:175], v112, s[6:7]
	global_load_dwordx2 v[168:169], v112, s[4:5]
	v_add_u32_e32 v112, 0x3000, v112
	global_load_dwordx2 v[170:171], v112, s[4:5]
	v_add_u32_e32 v112, 0x3000, v112
	global_load_dwordx2 v[172:173], v112, s[4:5]
	global_load_dwordx2 v[182:183], v113, s[6:7]
	global_load_dwordx2 v[176:177], v113, s[4:5]
	v_add_u32_e32 v113, 0x3000, v113
	global_load_dwordx2 v[178:179], v113, s[4:5]
	v_add_u32_e32 v113, 0x3000, v113
	global_load_dwordx2 v[180:181], v113, s[4:5]
	v_mov_b32_e32 v105, v104
	global_load_dwordx4 v[136:139], v105, s[16:17] nt
	v_add_u32_e32 v105, 0x30000, v105
	global_load_dwordx4 v[140:143], v105, s[16:17] nt
	v_add_u32_e32 v105, 0x30000, v105
	global_load_dwordx4 v[144:147], v105, s[16:17] nt
	v_add_u32_e32 v105, 0x30000, v105
	global_load_dwordx4 v[148:151], v105, s[16:17] nt
	s_add_u32 s10, s10, s13
	s_add_u32 s12, s12, s14
	s_cmp_ge_u32 s10, 24
	s_cbranch_scc0 .LcT2_nw6
	s_sub_u32 s10, s10, 24
	s_add_u32 s12, s12, 1
.LcT2_nw6:
	s_waitcnt lgkmcnt(0)
	s_barrier
	ds_read_b32 v123, v52 offset:32768
	ds_read2st64_b32 v[124:125], v53 offset0:128 offset1:129
	ds_read2st64_b32 v[126:127], v53 offset0:130 offset1:131
	ds_read2st64_b32 v[128:129], v53 offset0:132 offset1:133
	ds_read2st64_b32 v[130:131], v53 offset0:134 offset1:135
	ds_read_b32 v132, v54 offset:32768
	s_waitcnt lgkmcnt(0)
	v_cndmask_b32_e64 v123, 0, v123, s[20:21]
	v_cndmask_b32_e64 v132, 0, v132, s[22:23]
	v_lshlrev_b32_e32 v60, 16, v123
	v_and_b32_e32 v61, 0xffff0000, v123
	v_lshlrev_b32_e32 v62, 16, v124
	v_and_b32_e32 v63, 0xffff0000, v124
	v_lshlrev_b32_e32 v64, 16, v125
	v_and_b32_e32 v65, 0xffff0000, v125
	v_lshlrev_b32_e32 v66, 16, v126
	v_and_b32_e32 v67, 0xffff0000, v126
	v_lshlrev_b32_e32 v68, 16, v127
	v_and_b32_e32 v69, 0xffff0000, v127
	v_lshlrev_b32_e32 v70, 16, v128
	v_and_b32_e32 v71, 0xffff0000, v128
	v_lshlrev_b32_e32 v72, 16, v129
	v_and_b32_e32 v73, 0xffff0000, v129
	v_lshlrev_b32_e32 v74, 16, v130
	v_and_b32_e32 v75, 0xffff0000, v130
	v_lshlrev_b32_e32 v76, 16, v131
	v_and_b32_e32 v77, 0xffff0000, v131
	v_lshlrev_b32_e32 v78, 16, v132
	v_and_b32_e32 v79, 0xffff0000, v132
	v_pk_fma_f32 v[80:81], v[32:33], v[60:61], v[38:39]
	v_pk_fma_f32 v[82:83], v[32:33], v[62:63], v[38:39]
	v_pk_fma_f32 v[84:85], v[32:33], v[64:65], v[38:39]
	v_pk_fma_f32 v[86:87], v[32:33], v[66:67], v[38:39]
	v_pk_fma_f32 v[88:89], v[32:33], v[68:69], v[38:39]
	v_pk_fma_f32 v[90:91], v[32:33], v[70:71], v[38:39]
	v_pk_fma_f32 v[92:93], v[32:33], v[72:73], v[38:39]
	v_pk_fma_f32 v[94:95], v[32:33], v[74:75], v[38:39]
	v_pk_fma_f32 v[80:81], v[34:35], v[62:63], v[80:81]
	v_pk_fma_f32 v[82:83], v[34:35], v[64:65], v[82:83]
	v_pk_fma_f32 v[84:85], v[34:35], v[66:67], v[84:85]
	v_pk_fma_f32 v[86:87], v[34:35], v[68:69], v[86:87]
	v_pk_fma_f32 v[88:89], v[34:35], v[70:71], v[88:89]
	v_pk_fma_f32 v[90:91], v[34:35], v[72:73], v[90:91]
	v_pk_fma_f32 v[92:93], v[34:35], v[74:75], v[92:93]
	v_pk_fma_f32 v[94:95], v[34:35], v[76:77], v[94:95]
	v_pk_fma_f32 v[80:81], v[36:37], v[64:65], v[80:81]
	v_pk_fma_f32 v[82:83], v[36:37], v[66:67], v[82:83]
	v_pk_fma_f32 v[84:85], v[36:37], v[68:69], v[84:85]
	v_pk_fma_f32 v[86:87], v[36:37], v[70:71], v[86:87]
	v_pk_fma_f32 v[88:89], v[36:37], v[72:73], v[88:89]
	v_pk_fma_f32 v[90:91], v[36:37], v[74:75], v[90:91]
	v_pk_fma_f32 v[92:93], v[36:37], v[76:77], v[92:93]
	v_pk_fma_f32 v[94:95], v[36:37], v[78:79], v[94:95]
	v_cvt_pk_bf16_f32 v96, v80, v82
	v_cvt_pk_bf16_f32 v97, v84, v86
	v_cvt_pk_bf16_f32 v98, v88, v90
	v_cvt_pk_bf16_f32 v99, v92, v94
	v_cvt_pk_bf16_f32 v100, v81, v83
	v_cvt_pk_bf16_f32 v101, v85, v87
	v_cvt_pk_bf16_f32 v102, v89, v91
	v_cvt_pk_bf16_f32 v103, v93, v95
	global_store_dwordx4 v106, v[96:99], s[18:19]
	global_store_dwordx4 v107, v[100:103], s[18:19]
	ds_read_b32 v123, v55 offset:32768
	ds_read2st64_b32 v[124:125], v56 offset0:128 offset1:129
	ds_read2st64_b32 v[126:127], v56 offset0:130 offset1:131
	ds_read2st64_b32 v[128:129], v56 offset0:132 offset1:133
	ds_read2st64_b32 v[130:131], v56 offset0:134 offset1:135
	ds_read_b32 v132, v57 offset:32768
	s_waitcnt lgkmcnt(0)
	v_cndmask_b32_e64 v123, 0, v123, s[20:21]
	v_cndmask_b32_e64 v132, 0, v132, s[22:23]
	v_lshlrev_b32_e32 v60, 16, v123
	v_and_b32_e32 v61, 0xffff0000, v123
	v_lshlrev_b32_e32 v62, 16, v124
	v_and_b32_e32 v63, 0xffff0000, v124
	v_lshlrev_b32_e32 v64, 16, v125
	v_and_b32_e32 v65, 0xffff0000, v125
	v_lshlrev_b32_e32 v66, 16, v126
	v_and_b32_e32 v67, 0xffff0000, v126
	v_lshlrev_b32_e32 v68, 16, v127
	v_and_b32_e32 v69, 0xffff0000, v127
	v_lshlrev_b32_e32 v70, 16, v128
	v_and_b32_e32 v71, 0xffff0000, v128
	v_lshlrev_b32_e32 v72, 16, v129
	v_and_b32_e32 v73, 0xffff0000, v129
	v_lshlrev_b32_e32 v74, 16, v130
	v_and_b32_e32 v75, 0xffff0000, v130
	v_lshlrev_b32_e32 v76, 16, v131
	v_and_b32_e32 v77, 0xffff0000, v131
	v_lshlrev_b32_e32 v78, 16, v132
	v_and_b32_e32 v79, 0xffff0000, v132
	v_pk_fma_f32 v[80:81], v[40:41], v[60:61], v[46:47]
	v_pk_fma_f32 v[82:83], v[40:41], v[62:63], v[46:47]
	v_pk_fma_f32 v[84:85], v[40:41], v[64:65], v[46:47]
	v_pk_fma_f32 v[86:87], v[40:41], v[66:67], v[46:47]
	v_pk_fma_f32 v[88:89], v[40:41], v[68:69], v[46:47]
	v_pk_fma_f32 v[90:91], v[40:41], v[70:71], v[46:47]
	v_pk_fma_f32 v[92:93], v[40:41], v[72:73], v[46:47]
	v_pk_fma_f32 v[94:95], v[40:41], v[74:75], v[46:47]
	v_pk_fma_f32 v[80:81], v[42:43], v[62:63], v[80:81]
	v_pk_fma_f32 v[82:83], v[42:43], v[64:65], v[82:83]
	v_pk_fma_f32 v[84:85], v[42:43], v[66:67], v[84:85]
	v_pk_fma_f32 v[86:87], v[42:43], v[68:69], v[86:87]
	v_pk_fma_f32 v[88:89], v[42:43], v[70:71], v[88:89]
	v_pk_fma_f32 v[90:91], v[42:43], v[72:73], v[90:91]
	v_pk_fma_f32 v[92:93], v[42:43], v[74:75], v[92:93]
	v_pk_fma_f32 v[94:95], v[42:43], v[76:77], v[94:95]
	v_pk_fma_f32 v[80:81], v[44:45], v[64:65], v[80:81]
	v_pk_fma_f32 v[82:83], v[44:45], v[66:67], v[82:83]
	v_pk_fma_f32 v[84:85], v[44:45], v[68:69], v[84:85]
	v_pk_fma_f32 v[86:87], v[44:45], v[70:71], v[86:87]
	v_pk_fma_f32 v[88:89], v[44:45], v[72:73], v[88:89]
	v_pk_fma_f32 v[90:91], v[44:45], v[74:75], v[90:91]
	v_pk_fma_f32 v[92:93], v[44:45], v[76:77], v[92:93]
	v_pk_fma_f32 v[94:95], v[44:45], v[78:79], v[94:95]
	v_cvt_pk_bf16_f32 v96, v80, v82
	v_cvt_pk_bf16_f32 v97, v84, v86
	v_cvt_pk_bf16_f32 v98, v88, v90
	v_cvt_pk_bf16_f32 v99, v92, v94
	v_cvt_pk_bf16_f32 v100, v81, v83
	v_cvt_pk_bf16_f32 v101, v85, v87
	v_cvt_pk_bf16_f32 v102, v89, v91
	v_cvt_pk_bf16_f32 v103, v93, v95
	global_store_dwordx4 v108, v[96:99], s[18:19]
	global_store_dwordx4 v109, v[100:103], s[18:19]
	s_mov_b32 s0, 10
.LcT2_pair:
	s_lshr_b32 s24, s26, 3
	s_lshl_b32 s24, s24, 2
	s_lshr_b32 s25, s27, 6
	s_add_u32 s24, s24, s25
	s_lshl_b32 s24, s24, 24
	s_and_b32 s25, s26, 7
	s_lshl_b32 s25, s25, 21
	s_add_u32 s24, s24, s25
	s_and_b32 s25, s27, 63
	s_lshl_b32 s25, s25, 8
	s_add_u32 s24, s24, s25
	s_add_u32 s24, s24, 0x14000000
	s_add_u32 s18, s2, s24
	s_addc_u32 s19, s3, 0
	s_add_u32 s26, s26, s13
	s_add_u32 s27, s27, s14
	s_cmp_ge_u32 s26, 24
	s_cbranch_scc0 .LcT2_nw7
	s_sub_u32 s26, s26, 24
	s_add_u32 s27, s27, 1
.LcT2_nw7:
	s_waitcnt vmcnt(20)
	v_mov_b32_e32 v32, v16
	v_mov_b32_e32 v33, v17
	v_mov_b32_e32 v34, v18
	v_mov_b32_e32 v35, v19
	v_mov_b32_e32 v36, v20
	v_mov_b32_e32 v37, v21
	v_mov_b32_e32 v38, v22
	v_mov_b32_e32 v39, v23
	v_mov_b32_e32 v40, v24
	v_mov_b32_e32 v41, v25
	v_mov_b32_e32 v42, v26
	v_mov_b32_e32 v43, v27
	v_mov_b32_e32 v44, v28
	v_mov_b32_e32 v45, v29
	v_mov_b32_e32 v46, v30
	v_mov_b32_e32 v47, v31
	ds_write_b128 v48, v[0:3]
	ds_write_b128 v49, v[4:7]
	ds_write_b128 v50, v[8:11]
	ds_write_b128 v51, v[12:15]
	s_mul_i32 s24, s12, 0xC0000
	s_lshl_b32 s25, s10, 8
	s_add_u32 s24, s24, s25
	s_add_u32 s24, s24, 0x8000000
	s_add_u32 s16, s2, s24
	s_addc_u32 s17, s3, 0
	s_lshl_b32 s25, s10, 9
	v_add_u32_e32 v112, s25, v110
	v_add_u32_e32 v113, s25, v111
	global_load_dwordx2 v[22:23], v112, s[6:7]
	global_load_dwordx2 v[16:17], v112, s[4:5]
	v_add_u32_e32 v112, 0x3000, v112
	global_load_dwordx2 v[18:19], v112, s[4:5]
	v_add_u32_e32 v112, 0x3000, v112
	global_load_dwordx2 v[20:21], v112, s[4:5]
	global_load_dwordx2 v[30:31], v113, s[6:7]
	global_load_dwordx2 v[24:25], v113, s[4:5]
	v_add_u32_e32 v113, 0x3000, v113
	global_load_dwordx2 v[26:27], v113, s[4:5]
	v_add_u32_e32 v113, 0x3000, v113
	global_load_dwordx2 v[28:29], v113, s[4:5]
	v_mov_b32_e32 v105, v104
	global_load_dwordx4 v[0:3], v105, s[16:17] nt
	v_add_u32_e32 v105, 0x30000, v105
	global_load_dwordx4 v[4:7], v105, s[16:17] nt
	v_add_u32_e32 v105, 0x30000, v105
	global_load_dwordx4 v[8:11], v105, s[16:17] nt
	v_add_u32_e32 v105, 0x30000, v105
	global_load_dwordx4 v[12:15], v105, s[16:17] nt
	s_add_u32 s10, s10, s13
	s_add_u32 s12, s12, s14
	s_cmp_ge_u32 s10, 24
	s_cbranch_scc0 .LcT2_nw8
	s_sub_u32 s10, s10, 24
	s_add_u32 s12, s12, 1

.LcT2_nw9:
	s_waitcnt vmcnt(20)
	v_mov_b32_e32 v32, v168
	v_mov_b32_e32 v33, v169
	v_mov_b32_e32 v34, v170
	v_mov_b32_e32 v35, v171
	v_mov_b32_e32 v36, v172
	v_mov_b32_e32 v37, v173
	v_mov_b32_e32 v38, v174
	v_mov_b32_e32 v39, v175
	v_mov_b32_e32 v40, v176
	v_mov_b32_e32 v41, v177
	v_mov_b32_e32 v42, v178
	v_mov_b32_e32 v43, v179
	v_mov_b32_e32 v44, v180
	v_mov_b32_e32 v45, v181
	v_mov_b32_e32 v46, v182
	v_mov_b32_e32 v47, v183
	ds_write_b128 v48, v[136:139] offset:32768
	ds_write_b128 v49, v[140:143] offset:32768
	ds_write_b128 v50, v[144:147] offset:32768
	ds_write_b128 v51, v[148:151] offset:32768
	s_mul_i32 s24, s12, 0xC0000
	s_lshl_b32 s25, s10, 8
	s_add_u32 s24, s24, s25
	s_add_u32 s24, s24, 0x8000000
	s_add_u32 s16, s2, s24
	s_addc_u32 s17, s3, 0
	s_lshl_b32 s25, s10, 9
	v_add_u32_e32 v112, s25, v110
	v_add_u32_e32 v113, s25, v111
	global_load_dwordx2 v[174:175], v112, s[6:7]
	global_load_dwordx2 v[168:169], v112, s[4:5]
	v_add_u32_e32 v112, 0x3000, v112
	global_load_dwordx2 v[170:171], v112, s[4:5]
	v_add_u32_e32 v112, 0x3000, v112
	global_load_dwordx2 v[172:173], v112, s[4:5]
	global_load_dwordx2 v[182:183], v113, s[6:7]
	global_load_dwordx2 v[176:177], v113, s[4:5]
	v_add_u32_e32 v113, 0x3000, v113
	global_load_dwordx2 v[178:179], v113, s[4:5]
	v_add_u32_e32 v113, 0x3000, v113
	global_load_dwordx2 v[180:181], v113, s[4:5]
	v_mov_b32_e32 v105, v104
	global_load_dwordx4 v[136:139], v105, s[16:17] nt
	v_add_u32_e32 v105, 0x30000, v105
	global_load_dwordx4 v[140:143], v105, s[16:17] nt
	v_add_u32_e32 v105, 0x30000, v105
	global_load_dwordx4 v[144:147], v105, s[16:17] nt
	v_add_u32_e32 v105, 0x30000, v105
	global_load_dwordx4 v[148:151], v105, s[16:17] nt
	s_add_u32 s10, s10, s13
	s_add_u32 s12, s12, s14
	s_cmp_ge_u32 s10, 24
	s_cbranch_scc0 .LcT2_nw10
	s_sub_u32 s10, s10, 24
	s_add_u32 s12, s12, 1
.LcT2_nw10:
	s_waitcnt lgkmcnt(0)
	s_barrier
	ds_read_b32 v123, v52 offset:32768
	ds_read2st64_b32 v[124:125], v53 offset0:128 offset1:129
	ds_read2st64_b32 v[126:127], v53 offset0:130 offset1:131
	ds_read2st64_b32 v[128:129], v53 offset0:132 offset1:133
	ds_read2st64_b32 v[130:131], v53 offset0:134 offset1:135
	ds_read_b32 v132, v54 offset:32768
	s_waitcnt lgkmcnt(0)
	v_cndmask_b32_e64 v123, 0, v123, s[20:21]
	v_cndmask_b32_e64 v132, 0, v132, s[22:23]
	v_lshlrev_b32_e32 v60, 16, v123
	v_and_b32_e32 v61, 0xffff0000, v123
	v_lshlrev_b32_e32 v62, 16, v124
	v_and_b32_e32 v63, 0xffff0000, v124
	v_lshlrev_b32_e32 v64, 16, v125
	v_and_b32_e32 v65, 0xffff0000, v125
	v_lshlrev_b32_e32 v66, 16, v126
	v_and_b32_e32 v67, 0xffff0000, v126
	v_lshlrev_b32_e32 v68, 16, v127
	v_and_b32_e32 v69, 0xffff0000, v127
	v_lshlrev_b32_e32 v70, 16, v128
	v_and_b32_e32 v71, 0xffff0000, v128
	v_lshlrev_b32_e32 v72, 16, v129
	v_and_b32_e32 v73, 0xffff0000, v129
	v_lshlrev_b32_e32 v74, 16, v130
	v_and_b32_e32 v75, 0xffff0000, v130
	v_lshlrev_b32_e32 v76, 16, v131
	v_and_b32_e32 v77, 0xffff0000, v131
	v_lshlrev_b32_e32 v78, 16, v132
	v_and_b32_e32 v79, 0xffff0000, v132
	v_pk_fma_f32 v[80:81], v[32:33], v[60:61], v[38:39]
	v_pk_fma_f32 v[82:83], v[32:33], v[62:63], v[38:39]
	v_pk_fma_f32 v[84:85], v[32:33], v[64:65], v[38:39]
	v_pk_fma_f32 v[86:87], v[32:33], v[66:67], v[38:39]
	v_pk_fma_f32 v[88:89], v[32:33], v[68:69], v[38:39]
	v_pk_fma_f32 v[90:91], v[32:33], v[70:71], v[38:39]
	v_pk_fma_f32 v[92:93], v[32:33], v[72:73], v[38:39]
	v_pk_fma_f32 v[94:95], v[32:33], v[74:75], v[38:39]
	v_pk_fma_f32 v[80:81], v[34:35], v[62:63], v[80:81]
	v_pk_fma_f32 v[82:83], v[34:35], v[64:65], v[82:83]
	v_pk_fma_f32 v[84:85], v[34:35], v[66:67], v[84:85]
	v_pk_fma_f32 v[86:87], v[34:35], v[68:69], v[86:87]
	v_pk_fma_f32 v[88:89], v[34:35], v[70:71], v[88:89]
	v_pk_fma_f32 v[90:91], v[34:35], v[72:73], v[90:91]
	v_pk_fma_f32 v[92:93], v[34:35], v[74:75], v[92:93]
	v_pk_fma_f32 v[94:95], v[34:35], v[76:77], v[94:95]
	v_pk_fma_f32 v[80:81], v[36:37], v[64:65], v[80:81]
	v_pk_fma_f32 v[82:83], v[36:37], v[66:67], v[82:83]
	v_pk_fma_f32 v[84:85], v[36:37], v[68:69], v[84:85]
	v_pk_fma_f32 v[86:87], v[36:37], v[70:71], v[86:87]
	v_pk_fma_f32 v[88:89], v[36:37], v[72:73], v[88:89]
	v_pk_fma_f32 v[90:91], v[36:37], v[74:75], v[90:91]
	v_pk_fma_f32 v[92:93], v[36:37], v[76:77], v[92:93]
	v_pk_fma_f32 v[94:95], v[36:37], v[78:79], v[94:95]
	v_cvt_pk_bf16_f32 v96, v80, v82
	v_cvt_pk_bf16_f32 v97, v84, v86
	v_cvt_pk_bf16_f32 v98, v88, v90
	v_cvt_pk_bf16_f32 v99, v92, v94
	v_cvt_pk_bf16_f32 v100, v81, v83
	v_cvt_pk_bf16_f32 v101, v85, v87
	v_cvt_pk_bf16_f32 v102, v89, v91
	v_cvt_pk_bf16_f32 v103, v93, v95
	global_store_dwordx4 v106, v[96:99], s[18:19]
	global_store_dwordx4 v107, v[100:103], s[18:19]
	ds_read_b32 v123, v55 offset:32768
	ds_read2st64_b32 v[124:125], v56 offset0:128 offset1:129
	ds_read2st64_b32 v[126:127], v56 offset0:130 offset1:131
	ds_read2st64_b32 v[128:129], v56 offset0:132 offset1:133
	ds_read2st64_b32 v[130:131], v56 offset0:134 offset1:135
	ds_read_b32 v132, v57 offset:32768
	s_waitcnt lgkmcnt(0)
	v_cndmask_b32_e64 v123, 0, v123, s[20:21]
	v_cndmask_b32_e64 v132, 0, v132, s[22:23]
	v_lshlrev_b32_e32 v60, 16, v123
	v_and_b32_e32 v61, 0xffff0000, v123
	v_lshlrev_b32_e32 v62, 16, v124
	v_and_b32_e32 v63, 0xffff0000, v124
	v_lshlrev_b32_e32 v64, 16, v125
	v_and_b32_e32 v65, 0xffff0000, v125
	v_lshlrev_b32_e32 v66, 16, v126
	v_and_b32_e32 v67, 0xffff0000, v126
	v_lshlrev_b32_e32 v68, 16, v127
	v_and_b32_e32 v69, 0xffff0000, v127
	v_lshlrev_b32_e32 v70, 16, v128
	v_and_b32_e32 v71, 0xffff0000, v128
	v_lshlrev_b32_e32 v72, 16, v129
	v_and_b32_e32 v73, 0xffff0000, v129
	v_lshlrev_b32_e32 v74, 16, v130
	v_and_b32_e32 v75, 0xffff0000, v130
	v_lshlrev_b32_e32 v76, 16, v131
	v_and_b32_e32 v77, 0xffff0000, v131
	v_lshlrev_b32_e32 v78, 16, v132
	v_and_b32_e32 v79, 0xffff0000, v132
	v_pk_fma_f32 v[80:81], v[40:41], v[60:61], v[46:47]
	v_pk_fma_f32 v[82:83], v[40:41], v[62:63], v[46:47]
	v_pk_fma_f32 v[84:85], v[40:41], v[64:65], v[46:47]
	v_pk_fma_f32 v[86:87], v[40:41], v[66:67], v[46:47]
	v_pk_fma_f32 v[88:89], v[40:41], v[68:69], v[46:47]
	v_pk_fma_f32 v[90:91], v[40:41], v[70:71], v[46:47]
	v_pk_fma_f32 v[92:93], v[40:41], v[72:73], v[46:47]
	v_pk_fma_f32 v[94:95], v[40:41], v[74:75], v[46:47]
	v_pk_fma_f32 v[80:81], v[42:43], v[62:63], v[80:81]
	v_pk_fma_f32 v[82:83], v[42:43], v[64:65], v[82:83]
	v_pk_fma_f32 v[84:85], v[42:43], v[66:67], v[84:85]
	v_pk_fma_f32 v[86:87], v[42:43], v[68:69], v[86:87]
	v_pk_fma_f32 v[88:89], v[42:43], v[70:71], v[88:89]
	v_pk_fma_f32 v[90:91], v[42:43], v[72:73], v[90:91]
	v_pk_fma_f32 v[92:93], v[42:43], v[74:75], v[92:93]
	v_pk_fma_f32 v[94:95], v[42:43], v[76:77], v[94:95]
	v_pk_fma_f32 v[80:81], v[44:45], v[64:65], v[80:81]
	v_pk_fma_f32 v[82:83], v[44:45], v[66:67], v[82:83]
	v_pk_fma_f32 v[84:85], v[44:45], v[68:69], v[84:85]
	v_pk_fma_f32 v[86:87], v[44:45], v[70:71], v[86:87]
	v_pk_fma_f32 v[88:89], v[44:45], v[72:73], v[88:89]
	v_pk_fma_f32 v[90:91], v[44:45], v[74:75], v[90:91]
	v_pk_fma_f32 v[92:93], v[44:45], v[76:77], v[92:93]
	v_pk_fma_f32 v[94:95], v[44:45], v[78:79], v[94:95]
	v_cvt_pk_bf16_f32 v96, v80, v82
	v_cvt_pk_bf16_f32 v97, v84, v86
	v_cvt_pk_bf16_f32 v98, v88, v90
	v_cvt_pk_bf16_f32 v99, v92, v94
	v_cvt_pk_bf16_f32 v100, v81, v83
	v_cvt_pk_bf16_f32 v101, v85, v87
	v_cvt_pk_bf16_f32 v102, v89, v91
	v_cvt_pk_bf16_f32 v103, v93, v95
	global_store_dwordx4 v108, v[96:99], s[18:19]
	global_store_dwordx4 v109, v[100:103], s[18:19]
	s_sub_u32 s0, s0, 1
	s_cmp_lg_u32 s0, 0
	s_cbranch_scc1 .LcT2_pair
	s_lshr_b32 s24, s26, 3
	s_lshl_b32 s24, s24, 2
	s_lshr_b32 s25, s27, 6
	s_add_u32 s24, s24, s25
	s_lshl_b32 s24, s24, 24
	s_and_b32 s25, s26, 7
	s_lshl_b32 s25, s25, 21
	s_add_u32 s24, s24, s25
	s_and_b32 s25, s27, 63
	s_lshl_b32 s25, s25, 8
	s_add_u32 s24, s24, s25
	s_add_u32 s24, s24, 0x14000000
	s_add_u32 s18, s2, s24
	s_addc_u32 s19, s3, 0
	s_add_u32 s26, s26, s13
	s_add_u32 s27, s27, s14
	s_cmp_ge_u32 s26, 24
	s_cbranch_scc0 .LcT2_nw11
	s_sub_u32 s26, s26, 24
	s_add_u32 s27, s27, 1
.LcT2_nw11:
	s_waitcnt vmcnt(20)
	v_mov_b32_e32 v32, v16
	v_mov_b32_e32 v33, v17
	v_mov_b32_e32 v34, v18
	v_mov_b32_e32 v35, v19
	v_mov_b32_e32 v36, v20
	v_mov_b32_e32 v37, v21
	v_mov_b32_e32 v38, v22
	v_mov_b32_e32 v39, v23
	v_mov_b32_e32 v40, v24
	v_mov_b32_e32 v41, v25
	v_mov_b32_e32 v42, v26
	v_mov_b32_e32 v43, v27
	v_mov_b32_e32 v44, v28
	v_mov_b32_e32 v45, v29
	v_mov_b32_e32 v46, v30
	v_mov_b32_e32 v47, v31
	ds_write_b128 v48, v[0:3]
	ds_write_b128 v49, v[4:7]
	ds_write_b128 v50, v[8:11]
	ds_write_b128 v51, v[12:15]
	s_waitcnt lgkmcnt(0)
	s_barrier
	ds_read_b32 v123, v52
	ds_read2st64_b32 v[124:125], v53 offset0:0 offset1:1
	ds_read2st64_b32 v[126:127], v53 offset0:2 offset1:3
	ds_read2st64_b32 v[128:129], v53 offset0:4 offset1:5
	ds_read2st64_b32 v[130:131], v53 offset0:6 offset1:7
	ds_read_b32 v132, v54
	s_waitcnt lgkmcnt(0)
	v_cndmask_b32_e64 v123, 0, v123, s[20:21]
	v_cndmask_b32_e64 v132, 0, v132, s[22:23]
	v_lshlrev_b32_e32 v60, 16, v123
	v_and_b32_e32 v61, 0xffff0000, v123
	v_lshlrev_b32_e32 v62, 16, v124
	v_and_b32_e32 v63, 0xffff0000, v124
	v_lshlrev_b32_e32 v64, 16, v125
	v_and_b32_e32 v65, 0xffff0000, v125
	v_lshlrev_b32_e32 v66, 16, v126
	v_and_b32_e32 v67, 0xffff0000, v126
	v_lshlrev_b32_e32 v68, 16, v127
	v_and_b32_e32 v69, 0xffff0000, v127
	v_lshlrev_b32_e32 v70, 16, v128
	v_and_b32_e32 v71, 0xffff0000, v128
	v_lshlrev_b32_e32 v72, 16, v129
	v_and_b32_e32 v73, 0xffff0000, v129
	v_lshlrev_b32_e32 v74, 16, v130
	v_and_b32_e32 v75, 0xffff0000, v130
	v_lshlrev_b32_e32 v76, 16, v131
	v_and_b32_e32 v77, 0xffff0000, v131
	v_lshlrev_b32_e32 v78, 16, v132
	v_and_b32_e32 v79, 0xffff0000, v132
	v_pk_fma_f32 v[80:81], v[32:33], v[60:61], v[38:39]
	v_pk_fma_f32 v[82:83], v[32:33], v[62:63], v[38:39]
	v_pk_fma_f32 v[84:85], v[32:33], v[64:65], v[38:39]
	v_pk_fma_f32 v[86:87], v[32:33], v[66:67], v[38:39]
	v_pk_fma_f32 v[88:89], v[32:33], v[68:69], v[38:39]
	v_pk_fma_f32 v[90:91], v[32:33], v[70:71], v[38:39]
	v_pk_fma_f32 v[92:93], v[32:33], v[72:73], v[38:39]
	v_pk_fma_f32 v[94:95], v[32:33], v[74:75], v[38:39]
	v_pk_fma_f32 v[80:81], v[34:35], v[62:63], v[80:81]
	v_pk_fma_f32 v[82:83], v[34:35], v[64:65], v[82:83]
	v_pk_fma_f32 v[84:85], v[34:35], v[66:67], v[84:85]
	v_pk_fma_f32 v[86:87], v[34:35], v[68:69], v[86:87]
	v_pk_fma_f32 v[88:89], v[34:35], v[70:71], v[88:89]
	v_pk_fma_f32 v[90:91], v[34:35], v[72:73], v[90:91]
	v_pk_fma_f32 v[92:93], v[34:35], v[74:75], v[92:93]
	v_pk_fma_f32 v[94:95], v[34:35], v[76:77], v[94:95]
	v_pk_fma_f32 v[80:81], v[36:37], v[64:65], v[80:81]
	v_pk_fma_f32 v[82:83], v[36:37], v[66:67], v[82:83]
	v_pk_fma_f32 v[84:85], v[36:37], v[68:69], v[84:85]
	v_pk_fma_f32 v[86:87], v[36:37], v[70:71], v[86:87]
	v_pk_fma_f32 v[88:89], v[36:37], v[72:73], v[88:89]
	v_pk_fma_f32 v[90:91], v[36:37], v[74:75], v[90:91]
	v_pk_fma_f32 v[92:93], v[36:37], v[76:77], v[92:93]
	v_pk_fma_f32 v[94:95], v[36:37], v[78:79], v[94:95]
	v_cvt_pk_bf16_f32 v96, v80, v82
	v_cvt_pk_bf16_f32 v97, v84, v86
	v_cvt_pk_bf16_f32 v98, v88, v90
	v_cvt_pk_bf16_f32 v99, v92, v94
	v_cvt_pk_bf16_f32 v100, v81, v83
	v_cvt_pk_bf16_f32 v101, v85, v87
	v_cvt_pk_bf16_f32 v102, v89, v91
	v_cvt_pk_bf16_f32 v103, v93, v95
	global_store_dwordx4 v106, v[96:99], s[18:19]
	global_store_dwordx4 v107, v[100:103], s[18:19]
	ds_read_b32 v123, v55
	ds_read2st64_b32 v[124:125], v56 offset0:0 offset1:1
	ds_read2st64_b32 v[126:127], v56 offset0:2 offset1:3
	ds_read2st64_b32 v[128:129], v56 offset0:4 offset1:5
	ds_read2st64_b32 v[130:131], v56 offset0:6 offset1:7
	ds_read_b32 v132, v57
	s_waitcnt lgkmcnt(0)
	v_cndmask_b32_e64 v123, 0, v123, s[20:21]
	v_cndmask_b32_e64 v132, 0, v132, s[22:23]
	v_lshlrev_b32_e32 v60, 16, v123
	v_and_b32_e32 v61, 0xffff0000, v123
	v_lshlrev_b32_e32 v62, 16, v124
	v_and_b32_e32 v63, 0xffff0000, v124
	v_lshlrev_b32_e32 v64, 16, v125
	v_and_b32_e32 v65, 0xffff0000, v125
	v_lshlrev_b32_e32 v66, 16, v126
	v_and_b32_e32 v67, 0xffff0000, v126
	v_lshlrev_b32_e32 v68, 16, v127
	v_and_b32_e32 v69, 0xffff0000, v127
	v_lshlrev_b32_e32 v70, 16, v128
	v_and_b32_e32 v71, 0xffff0000, v128
	v_lshlrev_b32_e32 v72, 16, v129
	v_and_b32_e32 v73, 0xffff0000, v129
	v_lshlrev_b32_e32 v74, 16, v130
	v_and_b32_e32 v75, 0xffff0000, v130
	v_lshlrev_b32_e32 v76, 16, v131
	v_and_b32_e32 v77, 0xffff0000, v131
	v_lshlrev_b32_e32 v78, 16, v132
	v_and_b32_e32 v79, 0xffff0000, v132
	v_pk_fma_f32 v[80:81], v[40:41], v[60:61], v[46:47]
	v_pk_fma_f32 v[82:83], v[40:41], v[62:63], v[46:47]
	v_pk_fma_f32 v[84:85], v[40:41], v[64:65], v[46:47]
	v_pk_fma_f32 v[86:87], v[40:41], v[66:67], v[46:47]
	v_pk_fma_f32 v[88:89], v[40:41], v[68:69], v[46:47]
	v_pk_fma_f32 v[90:91], v[40:41], v[70:71], v[46:47]
	v_pk_fma_f32 v[92:93], v[40:41], v[72:73], v[46:47]
	v_pk_fma_f32 v[94:95], v[40:41], v[74:75], v[46:47]
	v_pk_fma_f32 v[80:81], v[42:43], v[62:63], v[80:81]
	v_pk_fma_f32 v[82:83], v[42:43], v[64:65], v[82:83]
	v_pk_fma_f32 v[84:85], v[42:43], v[66:67], v[84:85]
	v_pk_fma_f32 v[86:87], v[42:43], v[68:69], v[86:87]
	v_pk_fma_f32 v[88:89], v[42:43], v[70:71], v[88:89]
	v_pk_fma_f32 v[90:91], v[42:43], v[72:73], v[90:91]
	v_pk_fma_f32 v[92:93], v[42:43], v[74:75], v[92:93]
	v_pk_fma_f32 v[94:95], v[42:43], v[76:77], v[94:95]
	v_pk_fma_f32 v[80:81], v[44:45], v[64:65], v[80:81]
	v_pk_fma_f32 v[82:83], v[44:45], v[66:67], v[82:83]
	v_pk_fma_f32 v[84:85], v[44:45], v[68:69], v[84:85]
	v_pk_fma_f32 v[86:87], v[44:45], v[70:71], v[86:87]
	v_pk_fma_f32 v[88:89], v[44:45], v[72:73], v[88:89]
	v_pk_fma_f32 v[90:91], v[44:45], v[74:75], v[90:91]
	v_pk_fma_f32 v[92:93], v[44:45], v[76:77], v[92:93]
	v_pk_fma_f32 v[94:95], v[44:45], v[78:79], v[94:95]
	v_cvt_pk_bf16_f32 v96, v80, v82
	v_cvt_pk_bf16_f32 v97, v84, v86
	v_cvt_pk_bf16_f32 v98, v88, v90
	v_cvt_pk_bf16_f32 v99, v92, v94
	v_cvt_pk_bf16_f32 v100, v81, v83
	v_cvt_pk_bf16_f32 v101, v85, v87
	v_cvt_pk_bf16_f32 v102, v89, v91
	v_cvt_pk_bf16_f32 v103, v93, v95
	global_store_dwordx4 v108, v[96:99], s[18:19]
	global_store_dwordx4 v109, v[100:103], s[18:19]
	s_lshr_b32 s24, s26, 3
	s_lshl_b32 s24, s24, 2
	s_lshr_b32 s25, s27, 6
	s_add_u32 s24, s24, s25
	s_lshl_b32 s24, s24, 24
	s_and_b32 s25, s26, 7
	s_lshl_b32 s25, s25, 21
	s_add_u32 s24, s24, s25
	s_and_b32 s25, s27, 63
	s_lshl_b32 s25, s25, 8
	s_add_u32 s24, s24, s25
	s_add_u32 s24, s24, 0x14000000
	s_add_u32 s18, s2, s24
	s_addc_u32 s19, s3, 0
	s_add_u32 s26, s26, s13
	s_add_u32 s27, s27, s14
	s_cmp_ge_u32 s26, 24
	s_cbranch_scc0 .LcT2_nw12
	s_sub_u32 s26, s26, 24
	s_add_u32 s27, s27, 1
.LcT2_nw12:
	s_waitcnt vmcnt(8)
	v_mov_b32_e32 v32, v168
	v_mov_b32_e32 v33, v169
	v_mov_b32_e32 v34, v170
	v_mov_b32_e32 v35, v171
	v_mov_b32_e32 v36, v172
	v_mov_b32_e32 v37, v173
	v_mov_b32_e32 v38, v174
	v_mov_b32_e32 v39, v175
	v_mov_b32_e32 v40, v176
	v_mov_b32_e32 v41, v177
	v_mov_b32_e32 v42, v178
	v_mov_b32_e32 v43, v179
	v_mov_b32_e32 v44, v180
	v_mov_b32_e32 v45, v181
	v_mov_b32_e32 v46, v182
	v_mov_b32_e32 v47, v183
	ds_write_b128 v48, v[136:139] offset:32768
	ds_write_b128 v49, v[140:143] offset:32768
	ds_write_b128 v50, v[144:147] offset:32768
	ds_write_b128 v51, v[148:151] offset:32768
	s_waitcnt lgkmcnt(0)
	s_barrier
	ds_read_b32 v123, v52 offset:32768
	ds_read2st64_b32 v[124:125], v53 offset0:128 offset1:129
	ds_read2st64_b32 v[126:127], v53 offset0:130 offset1:131
	ds_read2st64_b32 v[128:129], v53 offset0:132 offset1:133
	ds_read2st64_b32 v[130:131], v53 offset0:134 offset1:135
	ds_read_b32 v132, v54 offset:32768
	s_waitcnt lgkmcnt(0)
	v_cndmask_b32_e64 v123, 0, v123, s[20:21]
	v_cndmask_b32_e64 v132, 0, v132, s[22:23]
	v_lshlrev_b32_e32 v60, 16, v123
	v_and_b32_e32 v61, 0xffff0000, v123
	v_lshlrev_b32_e32 v62, 16, v124
	v_and_b32_e32 v63, 0xffff0000, v124
	v_lshlrev_b32_e32 v64, 16, v125
	v_and_b32_e32 v65, 0xffff0000, v125
	v_lshlrev_b32_e32 v66, 16, v126
	v_and_b32_e32 v67, 0xffff0000, v126
	v_lshlrev_b32_e32 v68, 16, v127
	v_and_b32_e32 v69, 0xffff0000, v127
	v_lshlrev_b32_e32 v70, 16, v128
	v_and_b32_e32 v71, 0xffff0000, v128
	v_lshlrev_b32_e32 v72, 16, v129
	v_and_b32_e32 v73, 0xffff0000, v129
	v_lshlrev_b32_e32 v74, 16, v130
	v_and_b32_e32 v75, 0xffff0000, v130
	v_lshlrev_b32_e32 v76, 16, v131
	v_and_b32_e32 v77, 0xffff0000, v131
	v_lshlrev_b32_e32 v78, 16, v132
	v_and_b32_e32 v79, 0xffff0000, v132
	v_pk_fma_f32 v[80:81], v[32:33], v[60:61], v[38:39]
	v_pk_fma_f32 v[82:83], v[32:33], v[62:63], v[38:39]
	v_pk_fma_f32 v[84:85], v[32:33], v[64:65], v[38:39]
	v_pk_fma_f32 v[86:87], v[32:33], v[66:67], v[38:39]
	v_pk_fma_f32 v[88:89], v[32:33], v[68:69], v[38:39]
	v_pk_fma_f32 v[90:91], v[32:33], v[70:71], v[38:39]
	v_pk_fma_f32 v[92:93], v[32:33], v[72:73], v[38:39]
	v_pk_fma_f32 v[94:95], v[32:33], v[74:75], v[38:39]
	v_pk_fma_f32 v[80:81], v[34:35], v[62:63], v[80:81]
	v_pk_fma_f32 v[82:83], v[34:35], v[64:65], v[82:83]
	v_pk_fma_f32 v[84:85], v[34:35], v[66:67], v[84:85]
	v_pk_fma_f32 v[86:87], v[34:35], v[68:69], v[86:87]
	v_pk_fma_f32 v[88:89], v[34:35], v[70:71], v[88:89]
	v_pk_fma_f32 v[90:91], v[34:35], v[72:73], v[90:91]
	v_pk_fma_f32 v[92:93], v[34:35], v[74:75], v[92:93]
	v_pk_fma_f32 v[94:95], v[34:35], v[76:77], v[94:95]
	v_pk_fma_f32 v[80:81], v[36:37], v[64:65], v[80:81]
	v_pk_fma_f32 v[82:83], v[36:37], v[66:67], v[82:83]
	v_pk_fma_f32 v[84:85], v[36:37], v[68:69], v[84:85]
	v_pk_fma_f32 v[86:87], v[36:37], v[70:71], v[86:87]
	v_pk_fma_f32 v[88:89], v[36:37], v[72:73], v[88:89]
	v_pk_fma_f32 v[90:91], v[36:37], v[74:75], v[90:91]
	v_pk_fma_f32 v[92:93], v[36:37], v[76:77], v[92:93]
	v_pk_fma_f32 v[94:95], v[36:37], v[78:79], v[94:95]
	v_cvt_pk_bf16_f32 v96, v80, v82
	v_cvt_pk_bf16_f32 v97, v84, v86
	v_cvt_pk_bf16_f32 v98, v88, v90
	v_cvt_pk_bf16_f32 v99, v92, v94
	v_cvt_pk_bf16_f32 v100, v81, v83
	v_cvt_pk_bf16_f32 v101, v85, v87
	v_cvt_pk_bf16_f32 v102, v89, v91
	v_cvt_pk_bf16_f32 v103, v93, v95
	global_store_dwordx4 v106, v[96:99], s[18:19]
	global_store_dwordx4 v107, v[100:103], s[18:19]
	ds_read_b32 v123, v55 offset:32768
	ds_read2st64_b32 v[124:125], v56 offset0:128 offset1:129
	ds_read2st64_b32 v[126:127], v56 offset0:130 offset1:131
	ds_read2st64_b32 v[128:129], v56 offset0:132 offset1:133
	ds_read2st64_b32 v[130:131], v56 offset0:134 offset1:135
	ds_read_b32 v132, v57 offset:32768
	s_waitcnt lgkmcnt(0)
	v_cndmask_b32_e64 v123, 0, v123, s[20:21]
	v_cndmask_b32_e64 v132, 0, v132, s[22:23]
	v_lshlrev_b32_e32 v60, 16, v123
	v_and_b32_e32 v61, 0xffff0000, v123
	v_lshlrev_b32_e32 v62, 16, v124
	v_and_b32_e32 v63, 0xffff0000, v124
	v_lshlrev_b32_e32 v64, 16, v125
	v_and_b32_e32 v65, 0xffff0000, v125
	v_lshlrev_b32_e32 v66, 16, v126
	v_and_b32_e32 v67, 0xffff0000, v126
	v_lshlrev_b32_e32 v68, 16, v127
	v_and_b32_e32 v69, 0xffff0000, v127
	v_lshlrev_b32_e32 v70, 16, v128
	v_and_b32_e32 v71, 0xffff0000, v128
	v_lshlrev_b32_e32 v72, 16, v129
	v_and_b32_e32 v73, 0xffff0000, v129
	v_lshlrev_b32_e32 v74, 16, v130
	v_and_b32_e32 v75, 0xffff0000, v130
	v_lshlrev_b32_e32 v76, 16, v131
	v_and_b32_e32 v77, 0xffff0000, v131
	v_lshlrev_b32_e32 v78, 16, v132
	v_and_b32_e32 v79, 0xffff0000, v132
	v_pk_fma_f32 v[80:81], v[40:41], v[60:61], v[46:47]
	v_pk_fma_f32 v[82:83], v[40:41], v[62:63], v[46:47]
	v_pk_fma_f32 v[84:85], v[40:41], v[64:65], v[46:47]
	v_pk_fma_f32 v[86:87], v[40:41], v[66:67], v[46:47]
	v_pk_fma_f32 v[88:89], v[40:41], v[68:69], v[46:47]
	v_pk_fma_f32 v[90:91], v[40:41], v[70:71], v[46:47]
	v_pk_fma_f32 v[92:93], v[40:41], v[72:73], v[46:47]
	v_pk_fma_f32 v[94:95], v[40:41], v[74:75], v[46:47]
	v_pk_fma_f32 v[80:81], v[42:43], v[62:63], v[80:81]
	v_pk_fma_f32 v[82:83], v[42:43], v[64:65], v[82:83]
	v_pk_fma_f32 v[84:85], v[42:43], v[66:67], v[84:85]
	v_pk_fma_f32 v[86:87], v[42:43], v[68:69], v[86:87]
	v_pk_fma_f32 v[88:89], v[42:43], v[70:71], v[88:89]
	v_pk_fma_f32 v[90:91], v[42:43], v[72:73], v[90:91]
	v_pk_fma_f32 v[92:93], v[42:43], v[74:75], v[92:93]
	v_pk_fma_f32 v[94:95], v[42:43], v[76:77], v[94:95]
	v_pk_fma_f32 v[80:81], v[44:45], v[64:65], v[80:81]
	v_pk_fma_f32 v[82:83], v[44:45], v[66:67], v[82:83]
	v_pk_fma_f32 v[84:85], v[44:45], v[68:69], v[84:85]
	v_pk_fma_f32 v[86:87], v[44:45], v[70:71], v[86:87]
	v_pk_fma_f32 v[88:89], v[44:45], v[72:73], v[88:89]
	v_pk_fma_f32 v[90:91], v[44:45], v[74:75], v[90:91]
	v_pk_fma_f32 v[92:93], v[44:45], v[76:77], v[92:93]
	v_pk_fma_f32 v[94:95], v[44:45], v[78:79], v[94:95]
	v_cvt_pk_bf16_f32 v96, v80, v82
	v_cvt_pk_bf16_f32 v97, v84, v86
	v_cvt_pk_bf16_f32 v98, v88, v90
	v_cvt_pk_bf16_f32 v99, v92, v94
	v_cvt_pk_bf16_f32 v100, v81, v83
	v_cvt_pk_bf16_f32 v101, v85, v87
	v_cvt_pk_bf16_f32 v102, v89, v91
	v_cvt_pk_bf16_f32 v103, v93, v95
	global_store_dwordx4 v108, v[96:99], s[18:19]
	global_store_dwordx4 v109, v[100:103], s[18:19]
